# P8 role-B unit-transition barrier moved ahead of its epilogue so B's SwiGLU epilogue overlaps role A's first MFMA slot of the next unit
# baseline (speedup 1.0000x reference)
; #define PG8_STAGE(bufoff, gbase, voff) do { _Pragma("unroll") for (int _i = 0; _i < 2; ++_i) \
;         __builtin_amdgcn_global_load_lds((const unsigned*)((const char*)(gbase) + (voff)[_i]), (PG8_LAS unsigned*)(lds + (bufoff) + ldsw + _i * 8192), 16, 0, 0); } while (0)
; #define PG8_LDA(dst, b, h) do { _Pragma("unroll") for (int m = 0; m < 4; ++m) _Pragma("unroll") for (int k = 0; k < 2; ++k) dst[m][k] = *(const PG8_LAS bf16x8*)(lds + PG8_SA(b, h) + aoff + m * 2048 + k * 1024); } while (0)
; #define PG8_LDB(dst, b, h) do { _Pragma("unroll") for (int n = 0; n < 2; ++n) _Pragma("unroll") for (int k = 0; k < 2; ++k) dst[n][k] = *(const PG8_LAS bf16x8*)(lds + PG8_SB(b, h) + boff + n * 2048 + k * 1024); } while (0)
; #define PG8_MMA(ai, bj, At, Bt) do { __builtin_amdgcn_s_setprio(1); _Pragma("unroll") for (int m = 0; m < 4; ++m) _Pragma("unroll") for (int n = 0; n < 2; ++n) _Pragma("unroll") for (int k = 0; k < 2; ++k) \
;         acc[ai][bj][m][n] = __builtin_amdgcn_mfma_f32_16x16x32_bf16(Bt[n][k], At[m][k], acc[ai][bj][m][n], 0, 0, 0); __builtin_amdgcn_s_setprio(0); } while (0)
; template <class Epi, class Sched, bool ALIGN_EPI>
; __device__ __forceinline__ void gemm_phase(PG8_LAS unsigned char* lds, const Gemm g, const Sched& S, const Epi& E) {
;     ...
;             PG8_LDB(B0, 0, 0); PG8_LDB(B1, 0, 1); PG8_SCHED; PG8_LDA(At, 0, 0); PG8_STAGE(PG8_SA(1, 1), a1 + hstepA, voffA);
;             PG8_WAIT_V(8); PG8_WAIT_L(0); PG8_BAR; PG8_MMA(0, 0, At, B0); PG8_MMA(0, 1, At, B1); PG8_BAR; PG8_SCHED;
;             PG8_LDA(At, 0, 1); PG8_STAGE(PG8_SB(0, 0), b2, voffB); PG8_STAGE(PG8_SB(0, 1), b2 + hstepB, voffB); PG8_STAGE(PG8_SA(0, 0), a2, voffA);
;             PG8_WAIT_V(8); PG8_WAIT_L(0); PG8_BAR; PG8_MMA(1, 0, At, B0); PG8_MMA(1, 1, At, B1); PG8_BAR; PG8_SCHED;
;             PG8_LDB(B0, 1, 0); PG8_LDB(B1, 1, 1); PG8_SCHED; PG8_LDA(At, 1, 0); PG8_STAGE(PG8_SA(0, 1), a2 + hstepA, voffA);
;             PG8_WAIT_V(8); PG8_WAIT_L(0); PG8_BAR; PG8_MMA(0, 0, At, B0); PG8_MMA(0, 1, At, B1); PG8_BAR; PG8_SCHED;
;             PG8_LDA(At, 1, 1); PG8_STAGE(PG8_SB(1, 0), b3, voffB); PG8_STAGE(PG8_SB(1, 1), b3 + hstepB, voffB); PG8_STAGE(PG8_SA(1, 0), a3, voffA);
;             PG8_WAIT_V(8); PG8_WAIT_L(0); PG8_BAR; PG8_MMA(1, 0, At, B0); PG8_MMA(1, 1, At, B1); PG8_BAR; PG8_SCHED;
;     ...
;         if constexpr (ALIGN_EPI) { if (wr == 1) PG8_BAR; }
.Lp8k_B_init:
	s_setprio 1
	s_sub_u32 s28, s28, 0xa0000
	s_subb_u32 s29, s29, 0
	s_sub_u32 s50, s22, 0x20000
	s_subb_u32 s51, s23, 0
.Lp8k_B_nobar:
	ds_read_b128 v[190:193], v155 offset:0
	ds_read_b128 v[194:197], v155 offset:1024
	ds_read_b128 v[198:201], v155 offset:2048
	s_add_i32 m0, s2, 0xa000
	s_nop 0
	global_load_lds_dwordx4 v132, s[28:29]
	ds_read_b128 v[202:205], v155 offset:3072
	ds_read_b128 v[206:209], v155 offset:4096
	ds_read_b128 v[210:213], v155 offset:5120
	s_add_u32 s30, s28, 0x20000
	s_addc_u32 s31, s29, 0
	s_add_i32 m0, s2, 0xb000
	s_nop 0
	global_load_lds_dwordx4 v132, s[30:31]
	ds_read_b128 v[214:217], v155 offset:6144
	ds_read_b128 v[218:221], v155 offset:7168
	ds_read_b128 v[156:159], v153 offset:0
	s_add_u32 s30, s28, 0x80000
	s_addc_u32 s31, s29, 0
	s_add_i32 m0, s2, 0xe000
	s_nop 0
	global_load_lds_dwordx4 v132, s[30:31]
	ds_read_b128 v[160:163], v153 offset:1024
	ds_read_b128 v[164:167], v153 offset:2048
	ds_read_b128 v[168:171], v153 offset:3072
	s_add_u32 s30, s28, 0xa0000
	s_addc_u32 s31, s29, 0
	s_add_i32 m0, s2, 0xf000
	s_nop 0
	global_load_lds_dwordx4 v132, s[30:31]
	ds_read_b128 v[174:177], v153 offset:16384
	ds_read_b128 v[178:181], v153 offset:17408
	ds_read_b128 v[182:185], v153 offset:18432
	s_add_u32 s34, s28, 0x80
	s_addc_u32 s35, s29, 0
	s_cmp_eq_u32 s49, 15
	s_cselect_b32 s34, s50, s34
	s_cselect_b32 s35, s51, s35
	s_add_i32 m0, s2, 0x0
	s_nop 0
	global_load_lds_dwordx4 v136, s[34:35]
	ds_read_b128 v[186:189], v153 offset:19456
	ds_read_b128 v[222:225], v155 offset:16384
	ds_read_b128 v[226:229], v155 offset:17408
	s_add_u32 s30, s34, 0x20000
	s_addc_u32 s31, s35, 0
	s_add_i32 m0, s2, 0x1000
	s_nop 0
	global_load_lds_dwordx4 v136, s[30:31]
	ds_read_b128 v[230:233], v155 offset:18432
	ds_read_b128 v[234:237], v155 offset:19456
	ds_read_b128 v[238:241], v155 offset:20480
	s_add_u32 s30, s34, 0x80000
	s_addc_u32 s31, s35, 0
	s_add_i32 m0, s2, 0x4000
	s_nop 0
	global_load_lds_dwordx4 v136, s[30:31]
	ds_read_b128 v[242:245], v155 offset:21504
	ds_read_b128 v[246:249], v155 offset:22528
	ds_read_b128 v[250:253], v155 offset:23552
	s_add_u32 s30, s34, 0xa0000
	s_addc_u32 s31, s35, 0
	s_add_i32 m0, s2, 0x5000
	s_nop 0
	global_load_lds_dwordx4 v136, s[30:31]
	s_add_u32 s28, s28, 0x80
	s_addc_u32 s29, s29, 0
	s_waitcnt vmcnt(8) lgkmcnt(0)
	s_barrier
	v_mfma_f32_16x16x32_bf16 v[126:129], v[156:159], v[190:193], 0
	v_mfma_f32_16x16x32_bf16 v[126:129], v[160:163], v[194:197], v[126:129]
	v_mfma_f32_16x16x32_bf16 v[122:125], v[168:171], v[194:197], 0
	v_mfma_f32_16x16x32_bf16 v[122:125], v[164:167], v[190:193], v[122:125]
	v_mfma_f32_16x16x32_bf16 v[118:121], v[174:177], v[190:193], 0
	v_mfma_f32_16x16x32_bf16 v[118:121], v[178:181], v[194:197], v[118:121]
	v_mfma_f32_16x16x32_bf16 v[114:117], v[186:189], v[194:197], 0
	v_mfma_f32_16x16x32_bf16 v[114:117], v[182:185], v[190:193], v[114:117]
	v_mfma_f32_16x16x32_bf16 v[98:101], v[182:185], v[198:201], 0
	v_mfma_f32_16x16x32_bf16 v[98:101], v[186:189], v[202:205], v[98:101]
	v_mfma_f32_16x16x32_bf16 v[102:105], v[178:181], v[202:205], 0
	v_mfma_f32_16x16x32_bf16 v[102:105], v[174:177], v[198:201], v[102:105]
	v_mfma_f32_16x16x32_bf16 v[106:109], v[164:167], v[198:201], 0
	v_mfma_f32_16x16x32_bf16 v[106:109], v[168:171], v[202:205], v[106:109]
	v_mfma_f32_16x16x32_bf16 v[110:113], v[160:163], v[202:205], 0
	v_mfma_f32_16x16x32_bf16 v[110:113], v[156:159], v[198:201], v[110:113]
	v_mfma_f32_16x16x32_bf16 v[94:97], v[156:159], v[206:209], 0
	v_mfma_f32_16x16x32_bf16 v[94:97], v[160:163], v[210:213], v[94:97]
	v_mfma_f32_16x16x32_bf16 v[90:93], v[168:171], v[210:213], 0
	v_mfma_f32_16x16x32_bf16 v[90:93], v[164:167], v[206:209], v[90:93]
	v_mfma_f32_16x16x32_bf16 v[86:89], v[174:177], v[206:209], 0
	v_mfma_f32_16x16x32_bf16 v[86:89], v[178:181], v[210:213], v[86:89]
	v_mfma_f32_16x16x32_bf16 v[82:85], v[186:189], v[210:213], 0
	v_mfma_f32_16x16x32_bf16 v[82:85], v[182:185], v[206:209], v[82:85]
	v_mfma_f32_16x16x32_bf16 v[66:69], v[182:185], v[214:217], 0
	v_mfma_f32_16x16x32_bf16 v[66:69], v[186:189], v[218:221], v[66:69]
	v_mfma_f32_16x16x32_bf16 v[70:73], v[178:181], v[218:221], 0
	v_mfma_f32_16x16x32_bf16 v[70:73], v[174:177], v[214:217], v[70:73]
	v_mfma_f32_16x16x32_bf16 v[74:77], v[164:167], v[214:217], 0
	v_mfma_f32_16x16x32_bf16 v[74:77], v[168:171], v[218:221], v[74:77]
	v_mfma_f32_16x16x32_bf16 v[78:81], v[160:163], v[218:221], 0
	v_mfma_f32_16x16x32_bf16 v[78:81], v[156:159], v[214:217], v[78:81]
	v_mfma_f32_16x16x32_bf16 v[62:65], v[156:159], v[222:225], 0
	v_mfma_f32_16x16x32_bf16 v[62:65], v[160:163], v[226:229], v[62:65]
	v_mfma_f32_16x16x32_bf16 v[58:61], v[168:171], v[226:229], 0
	v_mfma_f32_16x16x32_bf16 v[58:61], v[164:167], v[222:225], v[58:61]
	v_mfma_f32_16x16x32_bf16 v[54:57], v[174:177], v[222:225], 0
	v_mfma_f32_16x16x32_bf16 v[54:57], v[178:181], v[226:229], v[54:57]
	v_mfma_f32_16x16x32_bf16 v[50:53], v[186:189], v[226:229], 0
	v_mfma_f32_16x16x32_bf16 v[50:53], v[182:185], v[222:225], v[50:53]
	v_mfma_f32_16x16x32_bf16 v[34:37], v[182:185], v[230:233], 0
	v_mfma_f32_16x16x32_bf16 v[34:37], v[186:189], v[234:237], v[34:37]
	v_mfma_f32_16x16x32_bf16 v[38:41], v[178:181], v[234:237], 0
	v_mfma_f32_16x16x32_bf16 v[38:41], v[174:177], v[230:233], v[38:41]
	v_mfma_f32_16x16x32_bf16 v[42:45], v[164:167], v[230:233], 0
	v_mfma_f32_16x16x32_bf16 v[42:45], v[168:171], v[234:237], v[42:45]
	v_mfma_f32_16x16x32_bf16 v[46:49], v[160:163], v[234:237], 0
	v_mfma_f32_16x16x32_bf16 v[46:49], v[156:159], v[230:233], v[46:49]
	v_mfma_f32_16x16x32_bf16 v[30:33], v[156:159], v[238:241], 0
	v_mfma_f32_16x16x32_bf16 v[30:33], v[160:163], v[242:245], v[30:33]
	v_mfma_f32_16x16x32_bf16 v[26:29], v[168:171], v[242:245], 0
	v_mfma_f32_16x16x32_bf16 v[26:29], v[164:167], v[238:241], v[26:29]
	v_mfma_f32_16x16x32_bf16 v[22:25], v[174:177], v[238:241], 0
	v_mfma_f32_16x16x32_bf16 v[22:25], v[178:181], v[242:245], v[22:25]
	v_mfma_f32_16x16x32_bf16 v[18:21], v[186:189], v[242:245], 0
	v_mfma_f32_16x16x32_bf16 v[18:21], v[182:185], v[238:241], v[18:21]
	v_mfma_f32_16x16x32_bf16 v[2:5], v[182:185], v[246:249], 0
	v_mfma_f32_16x16x32_bf16 v[2:5], v[186:189], v[250:253], v[2:5]
	v_mfma_f32_16x16x32_bf16 v[6:9], v[178:181], v[250:253], 0
	v_mfma_f32_16x16x32_bf16 v[6:9], v[174:177], v[246:249], v[6:9]
	v_mfma_f32_16x16x32_bf16 v[10:13], v[164:167], v[246:249], 0
	v_mfma_f32_16x16x32_bf16 v[10:13], v[168:171], v[250:253], v[10:13]
	v_mfma_f32_16x16x32_bf16 v[14:17], v[160:163], v[250:253], 0
	v_mfma_f32_16x16x32_bf16 v[14:17], v[156:159], v[246:249], v[14:17]
	s_waitcnt vmcnt(0)
	s_barrier
; #define PG8_STAGE(bufoff, gbase, voff) do { _Pragma("unroll") for (int _i = 0; _i < 2; ++_i) \
;         __builtin_amdgcn_global_load_lds((const unsigned*)((const char*)(gbase) + (voff)[_i]), (PG8_LAS unsigned*)(lds + (bufoff) + ldsw + _i * 8192), 16, 0, 0); } while (0)
; #define PG8_LDA(dst, b, h) do { _Pragma("unroll") for (int m = 0; m < 4; ++m) _Pragma("unroll") for (int k = 0; k < 2; ++k) dst[m][k] = *(const PG8_LAS bf16x8*)(lds + PG8_SA(b, h) + aoff + m * 2048 + k * 1024); } while (0)
; #define PG8_LDB(dst, b, h) do { _Pragma("unroll") for (int n = 0; n < 2; ++n) _Pragma("unroll") for (int k = 0; k < 2; ++k) dst[n][k] = *(const PG8_LAS bf16x8*)(lds + PG8_SB(b, h) + boff + n * 2048 + k * 1024); } while (0)
; #define PG8_MMA(ai, bj, At, Bt) do { __builtin_amdgcn_s_setprio(1); _Pragma("unroll") for (int m = 0; m < 4; ++m) _Pragma("unroll") for (int n = 0; n < 2; ++n) _Pragma("unroll") for (int k = 0; k < 2; ++k) \
;         acc[ai][bj][m][n] = __builtin_amdgcn_mfma_f32_16x16x32_bf16(Bt[n][k], At[m][k], acc[ai][bj][m][n], 0, 0, 0); __builtin_amdgcn_s_setprio(0); } while (0)
; #define PG8_WAIT_V(n) asm volatile("s_waitcnt vmcnt(" #n ")" ::: "memory")
; #define PG8_WAIT_L(n) asm volatile("s_waitcnt lgkmcnt(" #n ")" ::: "memory")
; #define PG8_BAR __builtin_amdgcn_s_barrier()
; #define PG8_SCHED __builtin_amdgcn_sched_barrier(0)
; template <class Epi, class Sched, bool ALIGN_EPI>
; __device__ __forceinline__ void gemm_phase(PG8_LAS unsigned char* lds, const Gemm g, const Sched& S, const Epi& E) {
;     ...
;             PG8_LDA(At, 0, 1); PG8_STAGE(PG8_SB(0, 0), b2, voffB); PG8_STAGE(PG8_SB(0, 1), b2 + hstepB, voffB); PG8_STAGE(PG8_SA(0, 0), a2, voffA);
;             PG8_WAIT_V(8); PG8_WAIT_L(0); PG8_BAR; PG8_MMA(1, 0, At, B0); PG8_MMA(1, 1, At, B1); PG8_BAR; PG8_SCHED;
;             PG8_LDB(B0, 1, 0); PG8_LDB(B1, 1, 1); PG8_SCHED; PG8_LDA(At, 1, 0); PG8_STAGE(PG8_SA(0, 1), a2 + hstepA, voffA);
;             PG8_WAIT_V(8); PG8_WAIT_L(0); PG8_BAR; PG8_MMA(0, 0, At, B0); PG8_MMA(0, 1, At, B1); PG8_BAR; PG8_SCHED;
;             PG8_LDA(At, 1, 1); PG8_STAGE(PG8_SB(1, 0), b3, voffB); PG8_STAGE(PG8_SB(1, 1), b3 + hstepB, voffB); PG8_STAGE(PG8_SA(1, 0), a3, voffA);
;             PG8_WAIT_V(8); PG8_WAIT_L(0); PG8_BAR; PG8_MMA(1, 0, At, B0); PG8_MMA(1, 1, At, B1); PG8_BAR; PG8_SCHED;
	ds_read_b128 v[190:193], v155 offset:32768
	ds_read_b128 v[194:197], v155 offset:33792
	ds_read_b128 v[198:201], v155 offset:34816
	s_cmp_eq_u32 s49, 15
	s_cselect_b32 s28, s50, s28
	s_cselect_b32 s29, s51, s29
	s_add_i32 m0, s2, 0x2000
	s_nop 0
	global_load_lds_dwordx4 v132, s[28:29]
	ds_read_b128 v[202:205], v155 offset:35840
	ds_read_b128 v[206:209], v155 offset:36864
	ds_read_b128 v[210:213], v155 offset:37888
	s_add_u32 s30, s28, 0x20000
	s_addc_u32 s31, s29, 0
	s_add_i32 m0, s2, 0x3000
	s_nop 0
	global_load_lds_dwordx4 v132, s[30:31]
	ds_read_b128 v[214:217], v155 offset:38912
	ds_read_b128 v[218:221], v155 offset:39936
	ds_read_b128 v[156:159], v153 offset:32768
	s_add_u32 s30, s28, 0x80000
	s_addc_u32 s31, s29, 0
	s_add_i32 m0, s2, 0x6000
	s_nop 0
	global_load_lds_dwordx4 v132, s[30:31]
	ds_read_b128 v[160:163], v153 offset:33792
	ds_read_b128 v[164:167], v153 offset:34816
	ds_read_b128 v[168:171], v153 offset:35840
	s_add_u32 s30, s28, 0xa0000
	s_addc_u32 s31, s29, 0
	s_add_i32 m0, s2, 0x7000
	s_nop 0
	global_load_lds_dwordx4 v132, s[30:31]
	ds_read_b128 v[174:177], v153 offset:49152
	ds_read_b128 v[178:181], v153 offset:50176
	ds_read_b128 v[182:185], v153 offset:51200
	s_add_u32 s34, s28, 0x80
	s_addc_u32 s35, s29, 0
	s_add_i32 m0, s2, 0x8000
	s_nop 0
	global_load_lds_dwordx4 v136, s[34:35]
	ds_read_b128 v[186:189], v153 offset:52224
	ds_read_b128 v[222:225], v155 offset:49152
	ds_read_b128 v[226:229], v155 offset:50176
	s_add_u32 s30, s34, 0x20000
	s_addc_u32 s31, s35, 0
	s_add_i32 m0, s2, 0x9000
	s_nop 0
	global_load_lds_dwordx4 v136, s[30:31]
	ds_read_b128 v[230:233], v155 offset:51200
	ds_read_b128 v[234:237], v155 offset:52224
	ds_read_b128 v[238:241], v155 offset:53248
	s_add_u32 s30, s34, 0x80000
	s_addc_u32 s31, s35, 0
	s_add_i32 m0, s2, 0xc000
	s_nop 0
	global_load_lds_dwordx4 v136, s[30:31]
	ds_read_b128 v[242:245], v155 offset:54272
	ds_read_b128 v[246:249], v155 offset:55296
	ds_read_b128 v[250:253], v155 offset:56320
	s_add_u32 s30, s34, 0xa0000
	s_addc_u32 s31, s35, 0
	s_add_i32 m0, s2, 0xd000
	s_nop 0
	global_load_lds_dwordx4 v136, s[30:31]
	s_add_u32 s28, s28, 0x80
	s_addc_u32 s29, s29, 0
	s_waitcnt vmcnt(8) lgkmcnt(0)
	s_barrier
	v_mfma_f32_16x16x32_bf16 v[126:129], v[156:159], v[190:193], v[126:129]
	v_mfma_f32_16x16x32_bf16 v[126:129], v[160:163], v[194:197], v[126:129]
	v_mfma_f32_16x16x32_bf16 v[122:125], v[168:171], v[194:197], v[122:125]
	v_mfma_f32_16x16x32_bf16 v[122:125], v[164:167], v[190:193], v[122:125]
	v_mfma_f32_16x16x32_bf16 v[118:121], v[174:177], v[190:193], v[118:121]
	v_mfma_f32_16x16x32_bf16 v[118:121], v[178:181], v[194:197], v[118:121]
	v_mfma_f32_16x16x32_bf16 v[114:117], v[186:189], v[194:197], v[114:117]
	v_mfma_f32_16x16x32_bf16 v[114:117], v[182:185], v[190:193], v[114:117]
	v_mfma_f32_16x16x32_bf16 v[98:101], v[182:185], v[198:201], v[98:101]
	v_mfma_f32_16x16x32_bf16 v[98:101], v[186:189], v[202:205], v[98:101]
	v_mfma_f32_16x16x32_bf16 v[102:105], v[178:181], v[202:205], v[102:105]
	v_mfma_f32_16x16x32_bf16 v[102:105], v[174:177], v[198:201], v[102:105]
	v_mfma_f32_16x16x32_bf16 v[106:109], v[164:167], v[198:201], v[106:109]
	v_mfma_f32_16x16x32_bf16 v[106:109], v[168:171], v[202:205], v[106:109]
	v_mfma_f32_16x16x32_bf16 v[110:113], v[160:163], v[202:205], v[110:113]
	v_mfma_f32_16x16x32_bf16 v[110:113], v[156:159], v[198:201], v[110:113]
	v_mfma_f32_16x16x32_bf16 v[94:97], v[156:159], v[206:209], v[94:97]
	v_mfma_f32_16x16x32_bf16 v[94:97], v[160:163], v[210:213], v[94:97]
	v_mfma_f32_16x16x32_bf16 v[90:93], v[168:171], v[210:213], v[90:93]
	v_mfma_f32_16x16x32_bf16 v[90:93], v[164:167], v[206:209], v[90:93]
	v_mfma_f32_16x16x32_bf16 v[86:89], v[174:177], v[206:209], v[86:89]
	v_mfma_f32_16x16x32_bf16 v[86:89], v[178:181], v[210:213], v[86:89]
	v_mfma_f32_16x16x32_bf16 v[82:85], v[186:189], v[210:213], v[82:85]
	v_mfma_f32_16x16x32_bf16 v[82:85], v[182:185], v[206:209], v[82:85]
	v_mfma_f32_16x16x32_bf16 v[66:69], v[182:185], v[214:217], v[66:69]
	v_mfma_f32_16x16x32_bf16 v[66:69], v[186:189], v[218:221], v[66:69]
	v_mfma_f32_16x16x32_bf16 v[70:73], v[178:181], v[218:221], v[70:73]
	v_mfma_f32_16x16x32_bf16 v[70:73], v[174:177], v[214:217], v[70:73]
	v_mfma_f32_16x16x32_bf16 v[74:77], v[164:167], v[214:217], v[74:77]
	v_mfma_f32_16x16x32_bf16 v[74:77], v[168:171], v[218:221], v[74:77]
	v_mfma_f32_16x16x32_bf16 v[78:81], v[160:163], v[218:221], v[78:81]
	v_mfma_f32_16x16x32_bf16 v[78:81], v[156:159], v[214:217], v[78:81]
	v_mfma_f32_16x16x32_bf16 v[62:65], v[156:159], v[222:225], v[62:65]
	v_mfma_f32_16x16x32_bf16 v[62:65], v[160:163], v[226:229], v[62:65]
	v_mfma_f32_16x16x32_bf16 v[58:61], v[168:171], v[226:229], v[58:61]
	v_mfma_f32_16x16x32_bf16 v[58:61], v[164:167], v[222:225], v[58:61]
	v_mfma_f32_16x16x32_bf16 v[54:57], v[174:177], v[222:225], v[54:57]
	v_mfma_f32_16x16x32_bf16 v[54:57], v[178:181], v[226:229], v[54:57]
	v_mfma_f32_16x16x32_bf16 v[50:53], v[186:189], v[226:229], v[50:53]
	v_mfma_f32_16x16x32_bf16 v[50:53], v[182:185], v[222:225], v[50:53]
	v_mfma_f32_16x16x32_bf16 v[34:37], v[182:185], v[230:233], v[34:37]
	v_mfma_f32_16x16x32_bf16 v[34:37], v[186:189], v[234:237], v[34:37]
	v_mfma_f32_16x16x32_bf16 v[38:41], v[178:181], v[234:237], v[38:41]
	v_mfma_f32_16x16x32_bf16 v[38:41], v[174:177], v[230:233], v[38:41]
	v_mfma_f32_16x16x32_bf16 v[42:45], v[164:167], v[230:233], v[42:45]
	v_mfma_f32_16x16x32_bf16 v[42:45], v[168:171], v[234:237], v[42:45]
	v_mfma_f32_16x16x32_bf16 v[46:49], v[160:163], v[234:237], v[46:49]
	v_mfma_f32_16x16x32_bf16 v[46:49], v[156:159], v[230:233], v[46:49]
	v_mfma_f32_16x16x32_bf16 v[30:33], v[156:159], v[238:241], v[30:33]
	v_mfma_f32_16x16x32_bf16 v[30:33], v[160:163], v[242:245], v[30:33]
	v_mfma_f32_16x16x32_bf16 v[26:29], v[168:171], v[242:245], v[26:29]
	v_mfma_f32_16x16x32_bf16 v[26:29], v[164:167], v[238:241], v[26:29]
	v_mfma_f32_16x16x32_bf16 v[22:25], v[174:177], v[238:241], v[22:25]
	v_mfma_f32_16x16x32_bf16 v[22:25], v[178:181], v[242:245], v[22:25]
	v_mfma_f32_16x16x32_bf16 v[18:21], v[186:189], v[242:245], v[18:21]
	v_mfma_f32_16x16x32_bf16 v[18:21], v[182:185], v[238:241], v[18:21]
	v_mfma_f32_16x16x32_bf16 v[2:5], v[182:185], v[246:249], v[2:5]
	v_mfma_f32_16x16x32_bf16 v[2:5], v[186:189], v[250:253], v[2:5]
	v_mfma_f32_16x16x32_bf16 v[6:9], v[178:181], v[250:253], v[6:9]
	v_mfma_f32_16x16x32_bf16 v[6:9], v[174:177], v[246:249], v[6:9]
	v_mfma_f32_16x16x32_bf16 v[10:13], v[164:167], v[246:249], v[10:13]
	v_mfma_f32_16x16x32_bf16 v[10:13], v[168:171], v[250:253], v[10:13]
	v_mfma_f32_16x16x32_bf16 v[14:17], v[160:163], v[250:253], v[14:17]
	v_mfma_f32_16x16x32_bf16 v[14:17], v[156:159], v[246:249], v[14:17]
	s_waitcnt vmcnt(0)
	s_barrier
	s_add_i32 s49, s49, 1

; #define PG8_BAR __builtin_amdgcn_s_barrier()
; template <class Epi, class Sched, bool ALIGN_EPI>
; __device__ __forceinline__ void gemm_phase(PG8_LAS unsigned char* lds, const Gemm g, const Sched& S, const Epi& E) {
;     ...
;         if constexpr (ALIGN_EPI) { if (wr == 0) PG8_BAR; }
;         E(acc, cur, wr, wc, fr, fq);
;         if (!has_next) break;
;     ...
;         if constexpr (ALIGN_EPI) { if (wr == 1) PG8_BAR; }
.Lp8k_B_exit:
	s_andn2_b64 vcc, exec, s[0:1]
	s_cbranch_vccnz .Lp8k_done
	s_barrier
